# rg_scan2 forward step loop: next step's RA row loaded one step ahead into a spare quad (no exposed load->vmcnt(0) per token step)
# baseline (speedup 1.0000x reference)
; __device__ __forceinline__ float rg_sp(float lam) { const float z = __expf(-lam); const float sp = z < 0.25f ? z * (1.0f - z * (0.5f - z * (0.33333334f - z * (0.25f - z * (0.2f - z * (0.16666667f - z * 0.14285715f)))))) : __logf(1.0f + z); return -8.0f * 1.4426950408889634f * sp; }
; __device__ __forceinline__ void rg_unpack8(const u32x4 w, float* v) { v[0] = bflo(w.x); v[1] = bfhi(w.x); v[2] = bflo(w.y); v[3] = bfhi(w.y); v[4] = bflo(w.z); v[5] = bfhi(w.z); v[6] = bflo(w.w); v[7] = bfhi(w.w); }
; __device__ __forceinline__ void rg_consts8(const float* bap, const float* bxp, const float* lamp, int idx, float* ba, float* bx, float* sp) {
; #pragma unroll
;     for (int h = 0; h < 2; ++h) { const f32x4 a = *(const f32x4*)(bap + idx + 4 * h), x = *(const f32x4*)(bxp + idx + 4 * h), l = *(const f32x4*)(lamp + idx + 4 * h);
; #pragma unroll
;         for (int e = 0; e < 4; ++e) { ba[4 * h + e] = a[e]; bx[4 * h + e] = x[e]; sp[4 * h + e] = rg_sp(l[e]); } }
; __device__ __forceinline__ void rg_scan2_phase(const bf16_t* RA0, bf16_t* RI0, const bf16_t* RA1, const bf16_t* RI1, const bf16_t* XCV, const float* bap, const float* bxp, const float* lamp, const float* CAR, bf16_t* Gb, int gtid, int ngt) {
;     ...
;         rg_fold8(CAR, b, 0, 2 * tc, cg, h); rg_consts8(bap, bxp, lamp, 8 * cg, ba, bx, sp);
; #pragma unroll 4
;         for (int i = 0; i < 64; ++i) { const size_t off = (size_t)(row0 + i) * DRNN + 8 * cg;
.LBB0_1247:
	s_andn2_saveexec_b64 s[6:7], s[24:25]
	v_fmamk_f32 v19, v20, 0xbe124925, v201
	v_fma_f32 v19, -v20, v19, s47
	v_fma_f32 v19, -v20, v19, s45
	v_fma_f32 v19, -v20, v19, s48
	v_fma_f32 v19, -v20, v19, 0.5
	v_fma_f32 v19, -v20, v19, 1.0
	v_mul_f32_e32 v19, v20, v19
	s_or_b64 exec, exec, s[6:7]
	s_movk_i32 s1, 0xa00
	v_lshlrev_b64 v[36:37], 1, v[30:31]
	v_mul_f32_e32 v68, 0xc138aa3b, v17
	v_mul_f32_e32 v69, 0xc138aa3b, v16
	v_mad_i64_i32 v[16:17], s[2:3], v22, s1, v[36:37]
	v_mul_f32_e32 v67, 0xc138aa3b, v18
	v_mul_f32_e32 v70, 0xc138aa3b, v26
	v_mul_f32_e32 v71, 0xc138aa3b, v25
	v_mul_f32_e32 v73, 0xc138aa3b, v24
	v_mul_f32_e32 v74, 0xc138aa3b, v23
	v_mul_f32_e32 v75, 0xc138aa3b, v19
	v_mad_i64_i32 v[32:33], s[2:3], v22, s1, 0
	v_lshl_add_u64 v[34:35], s[10:11], 0, v[16:17]
	s_mov_b64 s[6:7], 0
	s_mov_b64 s[100:101], 0xe400000
	v_lshl_add_u64 v[166:167], v[34:35], 0, s[100:101]
	global_load_dwordx4 v[162:165], v[166:167], off
	s_mov_b64 s[100:101], 0x1000
	s_waitcnt vmcnt(0)
	s_branch .LBB0_1251

; __device__ __forceinline__ unsigned pk2(float lo, float hi) { f32x2_pk v = {lo, hi}; bf16x2_pk b = __builtin_convertvector(v, bf16x2_pk); return __builtin_bit_cast(unsigned, b); }
; __device__ __forceinline__ float sigmoidf_(float x) { return __builtin_amdgcn_rcpf(1.0f + __expf(-x)); }
; __device__ __forceinline__ void rg_unpack8(const u32x4 w, float* v) { v[0] = bflo(w.x); v[1] = bfhi(w.x); v[2] = bflo(w.y); v[3] = bfhi(w.y); v[4] = bflo(w.z); v[5] = bfhi(w.z); v[6] = bflo(w.w); v[7] = bfhi(w.w); }
; __device__ __forceinline__ void rg_ab(float ra, float ri, float x, float ba, float bx, float sp, float& a, float& b) {
;     const float r = sigmoidf_(ra + ba), ig = sigmoidf_(ri + bx); const float l2 = r * sp; a = exp2f(l2);
;     const float x2 = 1.3862943611198906f * l2;
;     const float om = x2 > -0.125f ? -x2 * (1.0f + x2 * (0.5f + x2 * (0.16666667f + x2 * (0.041666668f + x2 * 0.0083333338f)))) : 1.0f - __expf(x2);
;     b = __builtin_amdgcn_sqrtf(om) * (ig * x);
; }
; __device__ __forceinline__ void rg_scan2_phase(const bf16_t* RA0, bf16_t* RI0, const bf16_t* RA1, const bf16_t* RI1, const bf16_t* XCV, const float* bap, const float* bxp, const float* lamp, const float* CAR, bf16_t* Gb, int gtid, int ngt) {
;     ...
;         for (int i = 0; i < 64; ++i) { const size_t off = (size_t)(row0 + i) * DRNN + 8 * cg;
;             float ra[8], ri[8], xv[8]; rg_unpack8(*(const u32x4*)(RA0 + off), ra); rg_unpack8(*(const u32x4*)(RI0 + off), ri); rg_unpack8(*(const u32x4*)(XCV + off), xv);
; #pragma unroll
;             for (int e = 0; e < 8; ++e) { float a, bb; rg_ab(ra[e], ri[e], xv[e], ba[e], bx[e], sp[e], a, bb); h[e] = a * h[e] + bb; }
;             u32x4 o; o.x = pk2(h[0], h[1]); o.y = pk2(h[2], h[3]); o.z = pk2(h[4], h[5]); o.w = pk2(h[6], h[7]); *(u32x4*)(RI0 + off) = o; }
.LBB0_1251:
	v_lshl_add_u64 v[38:39], v[34:35], 0, s[6:7]
	v_add_co_u32_e32 v16, vcc, 0xe400000, v38
	s_nop 1
	v_addc_co_u32_e32 v17, vcc, 0, v39, vcc
	s_nop 1
	v_mov_b32_e32 v24, v162
	v_mov_b32_e32 v25, v163
	v_mov_b32_e32 v26, v164
	v_mov_b32_e32 v27, v165
	global_load_dwordx4 v[162:165], v[16:17], off offset:2560
	v_add_co_u32_e32 v16, vcc, 0x13e00000, v38
	s_nop 0
	v_lshlrev_b32_e32 v31, 16, v24
	v_addc_co_u32_e32 v17, vcc, 0, v39, vcc
	v_add_co_u32_e32 v20, vcc, 0x8a00000, v38
	global_load_dwordx4 v[16:19], v[16:17], off
	s_nop 0
	v_addc_co_u32_e32 v21, vcc, 0, v39, vcc
	global_load_dwordx4 v[20:23], v[20:21], off
	v_add_f32_e32 v31, v0, v31
	v_mul_f32_e32 v31, 0xbfb8aa3b, v31
	v_exp_f32_e32 v31, v31
	s_nop 0
	v_add_f32_e32 v31, 1.0, v31
	v_rcp_f32_e32 v31, v31
	s_nop 0
	v_mul_f32_e32 v31, v74, v31
	v_mul_f32_e32 v43, 0x3fb17218, v31
	v_mul_f32_e32 v92, 0x3fb8aa3b, v43
	v_exp_f32_e32 v92, v92
	v_fmamk_f32 v93, v43, 0x3c088889, v202
	v_fmaak_f32 v93, v43, v93, 0x3e2aaaab
	v_fma_f32 v93, v43, v93, 0.5
	v_fma_f32 v93, v43, v93, 1.0
	v_mul_f32_e64 v93, v93, -v43
	v_sub_f32_e32 v92, 1.0, v92
	v_cmp_nlt_f32_e32 vcc, s5, v43
	s_nop 1
	v_cndmask_b32_e32 v41, v93, v92, vcc
	v_and_b32_e32 v24, 0xffff0000, v24
	v_add_f32_e32 v24, v1, v24
	v_mul_f32_e32 v24, 0xbfb8aa3b, v24
	v_exp_f32_e32 v24, v24
	s_nop 0
	v_add_f32_e32 v24, 1.0, v24
	v_rcp_f32_e32 v24, v24
	s_nop 0
	v_mul_f32_e32 v43, v73, v24
	v_mul_f32_e32 v24, 0x3fb17218, v43
	v_mul_f32_e32 v92, 0x3fb8aa3b, v24
	v_exp_f32_e32 v92, v92
	v_fmamk_f32 v93, v24, 0x3c088889, v202
	v_fmaak_f32 v93, v24, v93, 0x3e2aaaab
	v_fma_f32 v93, v24, v93, 0.5
	v_fma_f32 v93, v24, v93, 1.0
	v_mul_f32_e64 v93, v93, -v24
	v_sub_f32_e32 v92, 1.0, v92
	v_cmp_nlt_f32_e32 vcc, s5, v24
	s_nop 1
	v_cndmask_b32_e32 v59, v93, v92, vcc
	v_lshlrev_b32_e32 v24, 16, v25
	v_add_f32_e32 v24, v2, v24
	v_mul_f32_e32 v24, 0xbfb8aa3b, v24
	v_exp_f32_e32 v24, v24
	s_nop 0
	v_add_f32_e32 v24, 1.0, v24
	v_rcp_f32_e32 v24, v24
	s_nop 0
	v_mul_f32_e32 v45, v71, v24
	v_mul_f32_e32 v24, 0x3fb17218, v45
	v_mul_f32_e32 v92, 0x3fb8aa3b, v24
	v_exp_f32_e32 v92, v92
	v_fmamk_f32 v93, v24, 0x3c088889, v202
	v_fmaak_f32 v93, v24, v93, 0x3e2aaaab
	v_fma_f32 v93, v24, v93, 0.5
	v_fma_f32 v93, v24, v93, 1.0
	v_mul_f32_e64 v93, v93, -v24
	v_sub_f32_e32 v92, 1.0, v92
	v_cmp_nlt_f32_e32 vcc, s5, v24
	s_nop 1
	v_cndmask_b32_e32 v60, v93, v92, vcc
	v_and_b32_e32 v24, 0xffff0000, v25
	v_add_f32_e32 v24, v3, v24
	v_mul_f32_e32 v24, 0xbfb8aa3b, v24
	v_exp_f32_e32 v24, v24
	s_nop 0
	v_add_f32_e32 v24, 1.0, v24
	v_rcp_f32_e32 v24, v24
	s_nop 0
	v_mul_f32_e32 v61, v70, v24
	v_mul_f32_e32 v24, 0x3fb17218, v61
	v_mul_f32_e32 v92, 0x3fb8aa3b, v24
	v_exp_f32_e32 v92, v92
	v_fmamk_f32 v93, v24, 0x3c088889, v202
	v_fmaak_f32 v93, v24, v93, 0x3e2aaaab
	v_fma_f32 v93, v24, v93, 0.5
	v_fma_f32 v93, v24, v93, 1.0
	v_mul_f32_e64 v93, v93, -v24
	v_sub_f32_e32 v92, 1.0, v92
	v_cmp_nlt_f32_e32 vcc, s5, v24
	s_nop 1
	v_cndmask_b32_e32 v51, v93, v92, vcc
	v_lshlrev_b32_e32 v24, 16, v26
	v_add_f32_e32 v24, v8, v24
	v_mul_f32_e32 v24, 0xbfb8aa3b, v24
	v_exp_f32_e32 v24, v24
	s_nop 0
	v_add_f32_e32 v24, 1.0, v24
	v_rcp_f32_e32 v24, v24
	s_nop 0
	v_mul_f32_e32 v56, v69, v24
	v_mul_f32_e32 v24, 0x3fb17218, v56
	v_mul_f32_e32 v92, 0x3fb8aa3b, v24
	v_exp_f32_e32 v92, v92
	v_fmamk_f32 v93, v24, 0x3c088889, v202
	v_fmaak_f32 v93, v24, v93, 0x3e2aaaab
	v_fma_f32 v93, v24, v93, 0.5
	v_fma_f32 v93, v24, v93, 1.0
	v_mul_f32_e64 v93, v93, -v24
	v_sub_f32_e32 v92, 1.0, v92
	v_cmp_nlt_f32_e32 vcc, s5, v24
	s_nop 1
	v_cndmask_b32_e32 v49, v93, v92, vcc
	v_and_b32_e32 v24, 0xffff0000, v26
	v_add_f32_e32 v24, v9, v24
	v_mul_f32_e32 v24, 0xbfb8aa3b, v24
	v_exp_f32_e32 v24, v24
	s_nop 0
	v_add_f32_e32 v24, 1.0, v24
	v_rcp_f32_e32 v24, v24
	s_nop 0
	v_mul_f32_e32 v57, v68, v24
	v_mul_f32_e32 v24, 0x3fb17218, v57
	v_mul_f32_e32 v92, 0x3fb8aa3b, v24
	v_exp_f32_e32 v92, v92
	v_fmamk_f32 v93, v24, 0x3c088889, v202
	v_fmaak_f32 v93, v24, v93, 0x3e2aaaab
	v_fma_f32 v93, v24, v93, 0.5
	v_fma_f32 v93, v24, v93, 1.0
	v_mul_f32_e64 v93, v93, -v24
	v_sub_f32_e32 v92, 1.0, v92
	v_cmp_nlt_f32_e32 vcc, s5, v24
	s_nop 1
	v_cndmask_b32_e32 v47, v93, v92, vcc
	v_lshlrev_b32_e32 v24, 16, v27
	v_add_f32_e32 v24, v10, v24
	v_mul_f32_e32 v24, 0xbfb8aa3b, v24
	v_exp_f32_e32 v24, v24
	s_nop 0
	v_add_f32_e32 v24, 1.0, v24
	v_rcp_f32_e32 v24, v24
	s_nop 0
	v_mul_f32_e32 v54, v67, v24
	v_mul_f32_e32 v24, 0x3fb17218, v54
	v_mul_f32_e32 v92, 0x3fb8aa3b, v24
	v_exp_f32_e32 v92, v92
	v_fmamk_f32 v93, v24, 0x3c088889, v202
	v_fmaak_f32 v93, v24, v93, 0x3e2aaaab
	v_fma_f32 v93, v24, v93, 0.5
	v_fma_f32 v93, v24, v93, 1.0
	v_mul_f32_e64 v93, v93, -v24
	v_sub_f32_e32 v92, 1.0, v92
	v_cmp_nlt_f32_e32 vcc, s5, v24
	s_nop 1
	v_cndmask_b32_e32 v53, v93, v92, vcc
	v_and_b32_e32 v24, 0xffff0000, v27
	v_add_f32_e32 v24, v11, v24
	v_mul_f32_e32 v24, 0xbfb8aa3b, v24
	v_exp_f32_e32 v24, v24
	s_nop 0
	v_add_f32_e32 v24, 1.0, v24
	v_rcp_f32_e32 v24, v24
	s_nop 0
	v_mul_f32_e32 v27, v75, v24
	v_mul_f32_e32 v24, 0x3fb17218, v27
	v_mul_f32_e32 v92, 0x3fb8aa3b, v24
	v_exp_f32_e32 v92, v92
	v_fmamk_f32 v93, v24, 0x3c088889, v202
	v_fmaak_f32 v93, v24, v93, 0x3e2aaaab
	v_fma_f32 v93, v24, v93, 0.5
	v_fma_f32 v93, v24, v93, 1.0
	v_mul_f32_e64 v93, v93, -v24
	v_sub_f32_e32 v92, 1.0, v92
	v_cmp_nlt_f32_e32 vcc, s5, v24
	s_nop 1
	v_cndmask_b32_e32 v26, v93, v92, vcc
	v_cmp_gt_f32_e32 vcc, s82, v54
	s_mov_b64 s[2:3], 0x13e00000
	v_lshl_add_u64 v[24:25], v[38:39], 0, s[2:3]
	v_cndmask_b32_e32 v62, 0, v221, vcc
	v_add_f32_e32 v54, v54, v62
	v_exp_f32_e32 v54, v54
	v_cndmask_b32_e32 v55, 0, v220, vcc
	s_waitcnt vmcnt(0)
; __device__ __forceinline__ unsigned pk2(float lo, float hi) { f32x2_pk v = {lo, hi}; bf16x2_pk b = __builtin_convertvector(v, bf16x2_pk); return __builtin_bit_cast(unsigned, b); }
; __device__ __forceinline__ float sigmoidf_(float x) { return __builtin_amdgcn_rcpf(1.0f + __expf(-x)); }
; __device__ __forceinline__ void rg_unpack8(const u32x4 w, float* v) { v[0] = bflo(w.x); v[1] = bfhi(w.x); v[2] = bflo(w.y); v[3] = bfhi(w.y); v[4] = bflo(w.z); v[5] = bfhi(w.z); v[6] = bflo(w.w); v[7] = bfhi(w.w); }
; __device__ __forceinline__ void rg_ab(float ra, float ri, float x, float ba, float bx, float sp, float& a, float& b) {
;     const float r = sigmoidf_(ra + ba), ig = sigmoidf_(ri + bx); const float l2 = r * sp; a = exp2f(l2);
;     const float x2 = 1.3862943611198906f * l2;
;     const float om = x2 > -0.125f ? -x2 * (1.0f + x2 * (0.5f + x2 * (0.16666667f + x2 * (0.041666668f + x2 * 0.0083333338f)))) : 1.0f - __expf(x2);
;     b = __builtin_amdgcn_sqrtf(om) * (ig * x);
; }
; __device__ __forceinline__ void rg_scan2_phase(const bf16_t* RA0, bf16_t* RI0, const bf16_t* RA1, const bf16_t* RI1, const bf16_t* XCV, const float* bap, const float* bxp, const float* lamp, const float* CAR, bf16_t* Gb, int gtid, int ngt) {
;     ...
;         for (int i = 0; i < 64; ++i) { const size_t off = (size_t)(row0 + i) * DRNN + 8 * cg;
;             float ra[8], ri[8], xv[8]; rg_unpack8(*(const u32x4*)(RA0 + off), ra); rg_unpack8(*(const u32x4*)(RI0 + off), ri); rg_unpack8(*(const u32x4*)(XCV + off), xv);
; #pragma unroll
;             for (int e = 0; e < 8; ++e) { float a, bb; rg_ab(ra[e], ri[e], xv[e], ba[e], bx[e], sp[e], a, bb); h[e] = a * h[e] + bb; }
;             u32x4 o; o.x = pk2(h[0], h[1]); o.y = pk2(h[2], h[3]); o.z = pk2(h[4], h[5]); o.w = pk2(h[6], h[7]); *(u32x4*)(RI0 + off) = o; }
	v_lshlrev_b32_e32 v62, 16, v23
	v_cmp_gt_f32_e32 vcc, s82, v27
	v_ldexp_f32 v54, v54, v55
	v_lshlrev_b32_e32 v55, 16, v19
	v_add_f32_e32 v55, v14, v55
	v_mul_f32_e32 v55, 0xbfb8aa3b, v55
	v_exp_f32_e32 v55, v55
	s_mov_b32 s1, 0xe400000
	v_add_f32_e32 v55, 1.0, v55
	v_rcp_f32_e32 v63, v55
	v_sqrt_f32_e32 v55, v53
	v_mul_f32_e32 v53, v63, v62
	v_mul_f32_e32 v62, v53, v55
	v_pk_fma_f32 v[54:55], v[52:53], v[54:55], v[62:63] op_sel_hi:[1,1,0]
	v_cndmask_b32_e32 v53, 0, v221, vcc
	v_add_f32_e32 v27, v27, v53
	v_exp_f32_e32 v27, v27
	v_cndmask_b32_e32 v52, 0, v220, vcc
	v_cmp_gt_f32_e32 vcc, s82, v57
	v_sqrt_f32_e32 v53, v47
	v_ldexp_f32 v62, v27, v52
	v_cndmask_b32_e32 v52, 0, v221, vcc
	v_add_f32_e32 v52, v57, v52
	v_exp_f32_e32 v52, v52
	v_cndmask_b32_e32 v27, 0, v220, vcc
	v_and_b32_e32 v55, 0xffff0000, v22
	v_cmp_gt_f32_e32 vcc, s82, v56
	v_ldexp_f32 v52, v52, v27
	v_and_b32_e32 v27, 0xffff0000, v18
	v_add_f32_e32 v27, v13, v27
	v_mul_f32_e32 v27, 0xbfb8aa3b, v27
	v_exp_f32_e32 v27, v27
	v_lshlrev_b32_e32 v18, 16, v18
	v_add_f32_e32 v18, v12, v18
	v_mul_f32_e32 v18, 0xbfb8aa3b, v18
	v_add_f32_e32 v27, 1.0, v27
	v_exp_f32_e32 v18, v18
	v_rcp_f32_e32 v27, v27
	v_lshlrev_b32_e32 v22, 16, v22
	v_sqrt_f32_e32 v63, v26
	v_add_f32_e32 v18, 1.0, v18
	v_mul_f32_e32 v47, v27, v55
	v_rcp_f32_e32 v18, v18
	v_mul_f32_e32 v76, v47, v53
	v_pk_fma_f32 v[52:53], v[46:47], v[52:53], v[76:77] op_sel_hi:[1,1,0]
	v_cndmask_b32_e32 v46, 0, v221, vcc
	v_cndmask_b32_e32 v27, 0, v220, vcc
	v_add_f32_e32 v46, v56, v46
	v_cmp_gt_f32_e32 vcc, s82, v61
	v_exp_f32_e32 v46, v46
	v_sqrt_f32_e32 v47, v49
	v_mul_f32_e32 v49, v18, v22
	v_cndmask_b32_e32 v22, 0, v221, vcc
	v_add_f32_e32 v22, v61, v22
	v_exp_f32_e32 v22, v22
	v_ldexp_f32 v46, v46, v27
	v_mul_f32_e32 v18, v49, v47
	v_pk_fma_f32 v[56:57], v[48:49], v[46:47], v[18:19] op_sel_hi:[1,1,0]
	v_cndmask_b32_e32 v18, 0, v220, vcc
	v_ldexp_f32 v46, v22, v18
	v_and_b32_e32 v18, 0xffff0000, v17
	v_add_f32_e32 v18, v7, v18
	v_mul_f32_e32 v18, 0xbfb8aa3b, v18
	v_exp_f32_e32 v18, v18
	v_lshlrev_b32_e32 v17, 16, v17
	v_add_f32_e32 v17, v6, v17
	v_mul_f32_e32 v17, 0xbfb8aa3b, v17
	v_add_f32_e32 v18, 1.0, v18
	v_rcp_f32_e32 v18, v18
	v_exp_f32_e32 v17, v17
	v_and_b32_e32 v22, 0xffff0000, v21
	v_sqrt_f32_e32 v47, v51
	v_cmp_gt_f32_e32 vcc, s82, v45
	v_mul_f32_e32 v51, v18, v22
	v_add_f32_e32 v17, 1.0, v17
	v_cndmask_b32_e32 v22, 0, v221, vcc
	v_add_f32_e32 v22, v45, v22
	v_exp_f32_e32 v22, v22
	v_mul_f32_e32 v18, v51, v47
	v_rcp_f32_e32 v17, v17
	v_pk_fma_f32 v[50:51], v[50:51], v[46:47], v[18:19] op_sel_hi:[1,1,0]
	v_sqrt_f32_e32 v47, v60
	v_cndmask_b32_e32 v18, 0, v220, vcc
	v_ldexp_f32 v46, v22, v18
	v_lshlrev_b32_e32 v18, 16, v21
	v_mul_f32_e32 v45, v17, v18
	v_mul_f32_e32 v18, v45, v47
	v_cmp_gt_f32_e32 vcc, s82, v43
	v_pk_fma_f32 v[48:49], v[44:45], v[46:47], v[18:19] op_sel_hi:[1,1,0]
	v_sqrt_f32_e32 v45, v59
	v_cndmask_b32_e32 v18, 0, v221, vcc
	v_add_f32_e32 v18, v43, v18
	v_exp_f32_e32 v18, v18
	v_cndmask_b32_e32 v17, 0, v220, vcc
	v_cmp_gt_f32_e32 vcc, s82, v31
	v_ldexp_f32 v44, v18, v17
	v_and_b32_e32 v17, 0xffff0000, v16
	v_add_f32_e32 v17, v5, v17
	v_mul_f32_e32 v17, 0xbfb8aa3b, v17
	v_exp_f32_e32 v17, v17
	v_and_b32_e32 v18, 0xffff0000, v20
	v_add_f32_e32 v17, 1.0, v17
	v_rcp_f32_e32 v17, v17
	s_nop 0
	v_mul_f32_e32 v43, v17, v18
	v_lshlrev_b32_e32 v17, 16, v16
	v_mul_f32_e32 v18, v42, v44
	v_add_f32_e32 v17, v4, v17
	v_pk_fma_f32 v[46:47], v[42:43], v[44:45], v[18:19] op_sel_hi:[1,1,0]
	v_lshlrev_b32_e32 v18, 16, v20
	v_cndmask_b32_e32 v20, 0, v221, vcc
	v_mul_f32_e32 v17, 0xbfb8aa3b, v17
	v_add_f32_e32 v20, v31, v20
	v_exp_f32_e32 v17, v17
	v_exp_f32_e32 v20, v20
	v_cndmask_b32_e32 v16, 0, v220, vcc
	v_add_f32_e32 v17, 1.0, v17
	v_ldexp_f32 v16, v20, v16
	v_rcp_f32_e32 v20, v17
	v_sqrt_f32_e32 v17, v41
	v_mul_f32_e32 v41, v20, v18
	v_mul_f32_e32 v18, v41, v17
	v_pk_fma_f32 v[42:43], v[40:41], v[16:17], v[18:19] op_sel_hi:[1,1,0]
	v_and_b32_e32 v16, 0xffff0000, v19
	v_add_f32_e32 v16, v15, v16
	v_mul_f32_e32 v16, 0xbfb8aa3b, v16
	v_exp_f32_e32 v16, v16
	v_and_b32_e32 v17, 0xffff0000, v23
	v_cvt_pk_bf16_f32 v18, v56, v52
	v_add_f32_e32 v16, 1.0, v16
	v_rcp_f32_e32 v16, v16
	s_nop 0
	v_mul_f32_e32 v59, v16, v17
	v_mul_f32_e32 v16, v59, v63
	v_pk_fma_f32 v[40:41], v[58:59], v[62:63], v[16:17] op_sel_hi:[1,1,0]
	v_cvt_pk_bf16_f32 v16, v42, v47
	v_cvt_pk_bf16_f32 v17, v48, v50
	v_cvt_pk_bf16_f32 v19, v54, v40
	global_store_dwordx4 v[24:25], v[16:19], off
	s_nop 1
	v_add_co_u32_e32 v16, vcc, s1, v38
	s_mov_b32 s1, 0x13e00000
	s_nop 0
	v_addc_co_u32_e32 v17, vcc, 0, v39, vcc
	s_nop 1
	v_mov_b32_e32 v24, v162
	v_mov_b32_e32 v25, v163
	v_mov_b32_e32 v26, v164
	v_mov_b32_e32 v27, v165
	v_lshl_add_u64 v[166:167], v[16:17], 0, s[100:101]
	global_load_dwordx4 v[162:165], v[166:167], off offset:1024
	v_add_co_u32_e32 v16, vcc, s1, v38
	s_nop 0
	v_lshlrev_b32_e32 v31, 16, v24
	v_addc_co_u32_e32 v17, vcc, 0, v39, vcc
	v_add_co_u32_e32 v20, vcc, 0x8a00000, v38
	global_load_dwordx4 v[16:19], v[16:17], off offset:2560
	s_nop 0
	v_addc_co_u32_e32 v21, vcc, 0, v39, vcc
	global_load_dwordx4 v[20:23], v[20:21], off offset:2560
	v_add_f32_e32 v31, v0, v31
	v_mul_f32_e32 v31, 0xbfb8aa3b, v31
	v_exp_f32_e32 v31, v31
	s_nop 0
	v_add_f32_e32 v31, 1.0, v31
	v_rcp_f32_e32 v31, v31
	s_nop 0
	v_mul_f32_e32 v31, v74, v31
	v_mul_f32_e32 v43, 0x3fb17218, v31
	v_mul_f32_e32 v92, 0x3fb8aa3b, v43
	v_exp_f32_e32 v92, v92
	v_fmamk_f32 v93, v43, 0x3c088889, v202
	v_fmaak_f32 v93, v43, v93, 0x3e2aaaab
	v_fma_f32 v93, v43, v93, 0.5
	v_fma_f32 v93, v43, v93, 1.0
	v_mul_f32_e64 v93, v93, -v43
	v_sub_f32_e32 v92, 1.0, v92
	v_cmp_nlt_f32_e32 vcc, s5, v43
; __device__ __forceinline__ float sigmoidf_(float x) { return __builtin_amdgcn_rcpf(1.0f + __expf(-x)); }
; __device__ __forceinline__ void rg_ab(float ra, float ri, float x, float ba, float bx, float sp, float& a, float& b) {
;     const float r = sigmoidf_(ra + ba), ig = sigmoidf_(ri + bx); const float l2 = r * sp; a = exp2f(l2);
;     const float x2 = 1.3862943611198906f * l2;
;     const float om = x2 > -0.125f ? -x2 * (1.0f + x2 * (0.5f + x2 * (0.16666667f + x2 * (0.041666668f + x2 * 0.0083333338f)))) : 1.0f - __expf(x2);
;     b = __builtin_amdgcn_sqrtf(om) * (ig * x);
; }
	s_nop 1
	v_cndmask_b32_e32 v41, v93, v92, vcc
	v_and_b32_e32 v24, 0xffff0000, v24
	v_add_f32_e32 v24, v1, v24
	v_mul_f32_e32 v24, 0xbfb8aa3b, v24
	v_exp_f32_e32 v24, v24
	s_nop 0
	v_add_f32_e32 v24, 1.0, v24
	v_rcp_f32_e32 v24, v24
	s_nop 0
	v_mul_f32_e32 v43, v73, v24
	v_mul_f32_e32 v24, 0x3fb17218, v43
	v_mul_f32_e32 v92, 0x3fb8aa3b, v24
	v_exp_f32_e32 v92, v92
	v_fmamk_f32 v93, v24, 0x3c088889, v202
	v_fmaak_f32 v93, v24, v93, 0x3e2aaaab
	v_fma_f32 v93, v24, v93, 0.5
	v_fma_f32 v93, v24, v93, 1.0
	v_mul_f32_e64 v93, v93, -v24
	v_sub_f32_e32 v92, 1.0, v92
	v_cmp_nlt_f32_e32 vcc, s5, v24
	s_nop 1
	v_cndmask_b32_e32 v46, v93, v92, vcc
	v_lshlrev_b32_e32 v24, 16, v25
	v_add_f32_e32 v24, v2, v24
	v_mul_f32_e32 v24, 0xbfb8aa3b, v24
	v_exp_f32_e32 v24, v24
	s_nop 0
	v_add_f32_e32 v24, 1.0, v24
	v_rcp_f32_e32 v24, v24
	s_nop 0
	v_mul_f32_e32 v49, v71, v24
	v_mul_f32_e32 v24, 0x3fb17218, v49
	v_mul_f32_e32 v92, 0x3fb8aa3b, v24
	v_exp_f32_e32 v92, v92
	v_fmamk_f32 v93, v24, 0x3c088889, v202
	v_fmaak_f32 v93, v24, v93, 0x3e2aaaab
	v_fma_f32 v93, v24, v93, 0.5
	v_fma_f32 v93, v24, v93, 1.0
	v_mul_f32_e64 v93, v93, -v24
	v_sub_f32_e32 v92, 1.0, v92
	v_cmp_nlt_f32_e32 vcc, s5, v24
	s_nop 1
	v_cndmask_b32_e32 v58, v93, v92, vcc
	v_and_b32_e32 v24, 0xffff0000, v25
	v_add_f32_e32 v24, v3, v24
	v_mul_f32_e32 v24, 0xbfb8aa3b, v24
	v_exp_f32_e32 v24, v24
	s_nop 0
	v_add_f32_e32 v24, 1.0, v24
	v_rcp_f32_e32 v24, v24
	s_nop 0
	v_mul_f32_e32 v59, v70, v24
	v_mul_f32_e32 v24, 0x3fb17218, v59
	v_mul_f32_e32 v92, 0x3fb8aa3b, v24
	v_exp_f32_e32 v92, v92
	v_fmamk_f32 v93, v24, 0x3c088889, v202
	v_fmaak_f32 v93, v24, v93, 0x3e2aaaab
	v_fma_f32 v93, v24, v93, 0.5
	v_fma_f32 v93, v24, v93, 1.0
	v_mul_f32_e64 v93, v93, -v24
	v_sub_f32_e32 v92, 1.0, v92
	v_cmp_nlt_f32_e32 vcc, s5, v24
	s_nop 1
	v_cndmask_b32_e32 v51, v93, v92, vcc
	v_lshlrev_b32_e32 v24, 16, v26
	v_add_f32_e32 v24, v8, v24
	v_mul_f32_e32 v24, 0xbfb8aa3b, v24
	v_exp_f32_e32 v24, v24
	s_nop 0
	v_add_f32_e32 v24, 1.0, v24
	v_rcp_f32_e32 v24, v24
	s_nop 0
	v_mul_f32_e32 v45, v69, v24
	v_mul_f32_e32 v24, 0x3fb17218, v45
	v_mul_f32_e32 v92, 0x3fb8aa3b, v24
	v_exp_f32_e32 v92, v92
	v_fmamk_f32 v93, v24, 0x3c088889, v202
	v_fmaak_f32 v93, v24, v93, 0x3e2aaaab
	v_fma_f32 v93, v24, v93, 0.5
	v_fma_f32 v93, v24, v93, 1.0
	v_mul_f32_e64 v93, v93, -v24
	v_sub_f32_e32 v92, 1.0, v92
	v_cmp_nlt_f32_e32 vcc, s5, v24
	s_nop 1
	v_cndmask_b32_e32 v44, v93, v92, vcc
	v_and_b32_e32 v24, 0xffff0000, v26
	v_add_f32_e32 v24, v9, v24
	v_mul_f32_e32 v24, 0xbfb8aa3b, v24
	v_exp_f32_e32 v24, v24
	s_nop 0
	v_add_f32_e32 v24, 1.0, v24
	v_rcp_f32_e32 v24, v24
	s_nop 0
	v_mul_f32_e32 v57, v68, v24
	v_mul_f32_e32 v24, 0x3fb17218, v57
	v_mul_f32_e32 v92, 0x3fb8aa3b, v24
	v_exp_f32_e32 v92, v92
	v_fmamk_f32 v93, v24, 0x3c088889, v202
	v_fmaak_f32 v93, v24, v93, 0x3e2aaaab
	v_fma_f32 v93, v24, v93, 0.5
	v_fma_f32 v93, v24, v93, 1.0
	v_mul_f32_e64 v93, v93, -v24
	v_sub_f32_e32 v92, 1.0, v92
	v_cmp_nlt_f32_e32 vcc, s5, v24
	s_nop 1
	v_cndmask_b32_e32 v53, v93, v92, vcc
	v_lshlrev_b32_e32 v24, 16, v27
	v_add_f32_e32 v24, v10, v24
	v_mul_f32_e32 v24, 0xbfb8aa3b, v24
	v_exp_f32_e32 v24, v24
	s_nop 0
	v_add_f32_e32 v24, 1.0, v24
	v_rcp_f32_e32 v24, v24
	s_nop 0
	v_mul_f32_e32 v60, v67, v24
	v_mul_f32_e32 v24, 0x3fb17218, v60
	v_mul_f32_e32 v92, 0x3fb8aa3b, v24
	v_exp_f32_e32 v92, v92
	v_fmamk_f32 v93, v24, 0x3c088889, v202
	v_fmaak_f32 v93, v24, v93, 0x3e2aaaab
	v_fma_f32 v93, v24, v93, 0.5
	v_fma_f32 v93, v24, v93, 1.0
	v_mul_f32_e64 v93, v93, -v24
	v_sub_f32_e32 v92, 1.0, v92
	v_cmp_nlt_f32_e32 vcc, s5, v24
	s_nop 1
	v_cndmask_b32_e32 v55, v93, v92, vcc
	v_and_b32_e32 v24, 0xffff0000, v27
	v_add_f32_e32 v24, v11, v24
	v_mul_f32_e32 v24, 0xbfb8aa3b, v24
	v_exp_f32_e32 v24, v24
	s_nop 0
	v_add_f32_e32 v24, 1.0, v24
	v_rcp_f32_e32 v24, v24
	s_nop 0
	v_mul_f32_e32 v27, v75, v24
	v_mul_f32_e32 v24, 0x3fb17218, v27
	v_mul_f32_e32 v92, 0x3fb8aa3b, v24
	v_exp_f32_e32 v92, v92
	v_fmamk_f32 v93, v24, 0x3c088889, v202
	v_fmaak_f32 v93, v24, v93, 0x3e2aaaab
	v_fma_f32 v93, v24, v93, 0.5
	v_fma_f32 v93, v24, v93, 1.0
	v_mul_f32_e64 v93, v93, -v24
	v_sub_f32_e32 v92, 1.0, v92
	v_cmp_nlt_f32_e32 vcc, s5, v24
	s_nop 1
	v_cndmask_b32_e32 v26, v93, v92, vcc
	v_cmp_gt_f32_e32 vcc, s82, v60
	v_sqrt_f32_e32 v77, v26
	s_mov_b32 s1, 0xe401000
	v_cndmask_b32_e32 v62, 0, v221, vcc
	v_add_f32_e32 v60, v60, v62
	v_exp_f32_e32 v60, v60
	v_cndmask_b32_e32 v61, 0, v220, vcc
	s_waitcnt vmcnt(0)
; __device__ __forceinline__ unsigned pk2(float lo, float hi) { f32x2_pk v = {lo, hi}; bf16x2_pk b = __builtin_convertvector(v, bf16x2_pk); return __builtin_bit_cast(unsigned, b); }
; __device__ __forceinline__ float sigmoidf_(float x) { return __builtin_amdgcn_rcpf(1.0f + __expf(-x)); }
; __device__ __forceinline__ void rg_unpack8(const u32x4 w, float* v) { v[0] = bflo(w.x); v[1] = bfhi(w.x); v[2] = bflo(w.y); v[3] = bfhi(w.y); v[4] = bflo(w.z); v[5] = bfhi(w.z); v[6] = bflo(w.w); v[7] = bfhi(w.w); }
; __device__ __forceinline__ void rg_ab(float ra, float ri, float x, float ba, float bx, float sp, float& a, float& b) {
;     const float r = sigmoidf_(ra + ba), ig = sigmoidf_(ri + bx); const float l2 = r * sp; a = exp2f(l2);
;     const float x2 = 1.3862943611198906f * l2;
;     const float om = x2 > -0.125f ? -x2 * (1.0f + x2 * (0.5f + x2 * (0.16666667f + x2 * (0.041666668f + x2 * 0.0083333338f)))) : 1.0f - __expf(x2);
;     b = __builtin_amdgcn_sqrtf(om) * (ig * x);
; }
; __device__ __forceinline__ void rg_scan2_phase(const bf16_t* RA0, bf16_t* RI0, const bf16_t* RA1, const bf16_t* RI1, const bf16_t* XCV, const float* bap, const float* bxp, const float* lamp, const float* CAR, bf16_t* Gb, int gtid, int ngt) {
;     ...
;         for (int i = 0; i < 64; ++i) { const size_t off = (size_t)(row0 + i) * DRNN + 8 * cg;
;             float ra[8], ri[8], xv[8]; rg_unpack8(*(const u32x4*)(RA0 + off), ra); rg_unpack8(*(const u32x4*)(RI0 + off), ri); rg_unpack8(*(const u32x4*)(XCV + off), xv);
; #pragma unroll
;             for (int e = 0; e < 8; ++e) { float a, bb; rg_ab(ra[e], ri[e], xv[e], ba[e], bx[e], sp[e], a, bb); h[e] = a * h[e] + bb; }
;             u32x4 o; o.x = pk2(h[0], h[1]); o.y = pk2(h[2], h[3]); o.z = pk2(h[4], h[5]); o.w = pk2(h[6], h[7]); *(u32x4*)(RI0 + off) = o; }
	v_lshlrev_b32_e32 v62, 16, v23
	v_cmp_gt_f32_e32 vcc, s82, v27
	v_ldexp_f32 v60, v60, v61
	v_lshlrev_b32_e32 v61, 16, v19
	v_add_f32_e32 v61, v14, v61
	v_mul_f32_e32 v61, 0xbfb8aa3b, v61
	v_exp_f32_e32 v61, v61
	s_mov_b64 s[2:3], 0x13e00a00
	v_lshl_add_u64 v[24:25], v[38:39], 0, s[2:3]
	v_add_f32_e32 v61, 1.0, v61
	v_rcp_f32_e32 v63, v61
	v_sqrt_f32_e32 v61, v55
	v_mul_f32_e32 v55, v63, v62
	v_mul_f32_e32 v62, v55, v61
	v_pk_fma_f32 v[54:55], v[54:55], v[60:61], v[62:63] op_sel_hi:[1,1,0]
	v_cndmask_b32_e32 v60, 0, v221, vcc
	v_add_f32_e32 v27, v27, v60
	v_exp_f32_e32 v27, v27
	v_cndmask_b32_e32 v55, 0, v220, vcc
	v_cmp_gt_f32_e32 vcc, s82, v57
	v_sqrt_f32_e32 v61, v53
	v_ldexp_f32 v76, v27, v55
	v_cndmask_b32_e32 v55, 0, v221, vcc
	v_add_f32_e32 v55, v57, v55
	v_exp_f32_e32 v55, v55
	v_cndmask_b32_e32 v27, 0, v220, vcc
	v_cmp_gt_f32_e32 vcc, s82, v45
	v_ldexp_f32 v60, v55, v27
	v_and_b32_e32 v27, 0xffff0000, v18
	v_add_f32_e32 v27, v13, v27
	v_mul_f32_e32 v27, 0xbfb8aa3b, v27
	v_exp_f32_e32 v27, v27
	v_lshlrev_b32_e32 v18, 16, v18
	v_add_f32_e32 v18, v12, v18
	v_mul_f32_e32 v18, 0xbfb8aa3b, v18
	v_add_f32_e32 v27, 1.0, v27
	v_rcp_f32_e32 v27, v27
	v_exp_f32_e32 v18, v18
	v_and_b32_e32 v55, 0xffff0000, v22
	v_lshlrev_b32_e32 v22, 16, v22
	v_mul_f32_e32 v53, v27, v55
	v_add_f32_e32 v18, 1.0, v18
	v_mul_f32_e32 v62, v53, v61
	v_rcp_f32_e32 v18, v18
	v_pk_fma_f32 v[52:53], v[52:53], v[60:61], v[62:63] op_sel_hi:[1,1,0]
	v_cndmask_b32_e32 v27, 0, v220, vcc
	v_cndmask_b32_e32 v53, 0, v221, vcc
	v_add_f32_e32 v45, v45, v53
	v_cmp_gt_f32_e32 vcc, s82, v59
	v_exp_f32_e32 v45, v45
	v_sqrt_f32_e32 v61, v44
	v_mul_f32_e32 v57, v18, v22
	v_cndmask_b32_e32 v22, 0, v221, vcc
	v_add_f32_e32 v22, v59, v22
	v_exp_f32_e32 v22, v22
	v_ldexp_f32 v60, v45, v27
	v_mul_f32_e32 v18, v57, v61
	v_pk_fma_f32 v[44:45], v[56:57], v[60:61], v[18:19] op_sel_hi:[1,1,0]
	v_cndmask_b32_e32 v18, 0, v220, vcc
	v_ldexp_f32 v56, v22, v18
	v_and_b32_e32 v18, 0xffff0000, v17
	v_add_f32_e32 v18, v7, v18
	v_mul_f32_e32 v18, 0xbfb8aa3b, v18
	v_exp_f32_e32 v18, v18
	v_lshlrev_b32_e32 v17, 16, v17
	v_add_f32_e32 v17, v6, v17
	v_mul_f32_e32 v17, 0xbfb8aa3b, v17
	v_add_f32_e32 v18, 1.0, v18
	v_rcp_f32_e32 v18, v18
	v_exp_f32_e32 v17, v17
	v_and_b32_e32 v22, 0xffff0000, v21
	v_sqrt_f32_e32 v57, v51
	v_cmp_gt_f32_e32 vcc, s82, v49
	v_mul_f32_e32 v51, v18, v22
	v_add_f32_e32 v17, 1.0, v17
	v_cndmask_b32_e32 v22, 0, v221, vcc
	v_add_f32_e32 v22, v49, v22
	v_exp_f32_e32 v22, v22
	v_mul_f32_e32 v18, v51, v57
	v_rcp_f32_e32 v17, v17
	v_pk_fma_f32 v[60:61], v[50:51], v[56:57], v[18:19] op_sel_hi:[1,1,0]
	v_sqrt_f32_e32 v51, v58
	v_cndmask_b32_e32 v18, 0, v220, vcc
	v_ldexp_f32 v50, v22, v18
	v_lshlrev_b32_e32 v18, 16, v21
	v_mul_f32_e32 v49, v17, v18
	v_mul_f32_e32 v18, v49, v51
	v_cmp_gt_f32_e32 vcc, s82, v43
	v_pk_fma_f32 v[58:59], v[48:49], v[50:51], v[18:19] op_sel_hi:[1,1,0]
	v_sqrt_f32_e32 v49, v46
	v_cndmask_b32_e32 v18, 0, v221, vcc
	v_add_f32_e32 v18, v43, v18
	v_exp_f32_e32 v18, v18
	v_cndmask_b32_e32 v17, 0, v220, vcc
	v_mov_b32_e32 v50, v47
	v_cmp_gt_f32_e32 vcc, s82, v31
	v_ldexp_f32 v48, v18, v17
	v_and_b32_e32 v17, 0xffff0000, v16
	v_add_f32_e32 v17, v5, v17
	v_mul_f32_e32 v17, 0xbfb8aa3b, v17
	v_exp_f32_e32 v17, v17
	v_and_b32_e32 v18, 0xffff0000, v20
	v_add_f32_e32 v17, 1.0, v17
	v_rcp_f32_e32 v17, v17
	s_nop 0
	v_mul_f32_e32 v51, v17, v18
	v_lshlrev_b32_e32 v17, 16, v16
	v_mul_f32_e32 v18, v47, v48
	v_add_f32_e32 v17, v4, v17
	v_pk_fma_f32 v[62:63], v[50:51], v[48:49], v[18:19] op_sel_hi:[1,1,0]
	v_lshlrev_b32_e32 v18, 16, v20
	v_cndmask_b32_e32 v20, 0, v221, vcc
	v_mul_f32_e32 v17, 0xbfb8aa3b, v17
	v_add_f32_e32 v20, v31, v20
	v_exp_f32_e32 v17, v17
	v_exp_f32_e32 v20, v20
	v_cndmask_b32_e32 v16, 0, v220, vcc
	v_add_co_u32_e32 v48, vcc, s1, v38
	v_add_f32_e32 v17, 1.0, v17
	v_ldexp_f32 v16, v20, v16
	v_rcp_f32_e32 v20, v17
	v_sqrt_f32_e32 v17, v41
	v_addc_co_u32_e32 v49, vcc, 0, v39, vcc
	v_mul_f32_e32 v43, v20, v18
	v_mul_f32_e32 v18, v43, v17
	v_pk_fma_f32 v[56:57], v[42:43], v[16:17], v[18:19] op_sel_hi:[1,1,0]
	v_and_b32_e32 v16, 0xffff0000, v19
	v_add_f32_e32 v16, v15, v16
	v_mul_f32_e32 v16, 0xbfb8aa3b, v16
	v_exp_f32_e32 v16, v16
	v_and_b32_e32 v17, 0xffff0000, v23
	v_cvt_pk_bf16_f32 v18, v44, v52
	s_mov_b32 s1, 0x13e01000
	v_add_f32_e32 v16, 1.0, v16
	v_rcp_f32_e32 v16, v16
	s_nop 0
	v_mul_f32_e32 v41, v16, v17
	v_mul_f32_e32 v16, v41, v77
	v_pk_fma_f32 v[50:51], v[40:41], v[76:77], v[16:17] op_sel_hi:[1,1,0]
	v_cvt_pk_bf16_f32 v16, v56, v63
	v_cvt_pk_bf16_f32 v17, v58, v60
	v_cvt_pk_bf16_f32 v19, v54, v50
	global_store_dwordx4 v[24:25], v[16:19], off
	s_nop 1
	v_mov_b32_e32 v24, v162
	v_mov_b32_e32 v25, v163
	v_mov_b32_e32 v26, v164
	v_mov_b32_e32 v27, v165
	global_load_dwordx4 v[162:165], v[48:49], off offset:3584
	v_add_co_u32_e32 v40, vcc, s1, v38
	s_nop 0
	v_lshlrev_b32_e32 v31, 16, v24
	v_addc_co_u32_e32 v41, vcc, 0, v39, vcc
	v_add_co_u32_e32 v20, vcc, 0x8a01000, v38
	global_load_dwordx4 v[16:19], v[40:41], off offset:1024
	s_nop 0
	v_addc_co_u32_e32 v21, vcc, 0, v39, vcc
	global_load_dwordx4 v[20:23], v[20:21], off offset:1024
	v_add_f32_e32 v31, v0, v31
	v_mul_f32_e32 v31, 0xbfb8aa3b, v31
	v_exp_f32_e32 v31, v31
	s_nop 0
	v_add_f32_e32 v31, 1.0, v31
	v_rcp_f32_e32 v31, v31
	s_nop 0
	v_mul_f32_e32 v31, v74, v31
	v_mul_f32_e32 v42, 0x3fb17218, v31
	v_mul_f32_e32 v92, 0x3fb8aa3b, v42
	v_exp_f32_e32 v92, v92
	v_fmamk_f32 v93, v42, 0x3c088889, v202
	v_fmaak_f32 v93, v42, v93, 0x3e2aaaab
	v_fma_f32 v93, v42, v93, 0.5
	v_fma_f32 v93, v42, v93, 1.0
	v_mul_f32_e64 v93, v93, -v42
	v_sub_f32_e32 v92, 1.0, v92
	v_cmp_nlt_f32_e32 vcc, s5, v42
	s_nop 1
; __device__ __forceinline__ float sigmoidf_(float x) { return __builtin_amdgcn_rcpf(1.0f + __expf(-x)); }
; __device__ __forceinline__ void rg_ab(float ra, float ri, float x, float ba, float bx, float sp, float& a, float& b) {
;     const float r = sigmoidf_(ra + ba), ig = sigmoidf_(ri + bx); const float l2 = r * sp; a = exp2f(l2);
;     const float x2 = 1.3862943611198906f * l2;
;     const float om = x2 > -0.125f ? -x2 * (1.0f + x2 * (0.5f + x2 * (0.16666667f + x2 * (0.041666668f + x2 * 0.0083333338f)))) : 1.0f - __expf(x2);
;     b = __builtin_amdgcn_sqrtf(om) * (ig * x);
; }
	v_cndmask_b32_e32 v51, v93, v92, vcc
	v_and_b32_e32 v24, 0xffff0000, v24
	v_add_f32_e32 v24, v1, v24
	v_mul_f32_e32 v24, 0xbfb8aa3b, v24
	v_exp_f32_e32 v24, v24
	s_nop 0
	v_add_f32_e32 v24, 1.0, v24
	v_rcp_f32_e32 v24, v24
	s_nop 0
	v_mul_f32_e32 v57, v73, v24
	v_mul_f32_e32 v24, 0x3fb17218, v57
	v_mul_f32_e32 v92, 0x3fb8aa3b, v24
	v_exp_f32_e32 v92, v92
	v_fmamk_f32 v93, v24, 0x3c088889, v202
	v_fmaak_f32 v93, v24, v93, 0x3e2aaaab
	v_fma_f32 v93, v24, v93, 0.5
	v_fma_f32 v93, v24, v93, 1.0
	v_mul_f32_e64 v93, v93, -v24
	v_sub_f32_e32 v92, 1.0, v92
	v_cmp_nlt_f32_e32 vcc, s5, v24
	s_nop 1
	v_cndmask_b32_e32 v62, v93, v92, vcc
	v_lshlrev_b32_e32 v24, 16, v25
	v_add_f32_e32 v24, v2, v24
	v_mul_f32_e32 v24, 0xbfb8aa3b, v24
	v_exp_f32_e32 v24, v24
	s_nop 0
	v_add_f32_e32 v24, 1.0, v24
	v_rcp_f32_e32 v24, v24
	s_nop 0
	v_mul_f32_e32 v59, v71, v24
	v_mul_f32_e32 v24, 0x3fb17218, v59
	v_mul_f32_e32 v92, 0x3fb8aa3b, v24
	v_exp_f32_e32 v92, v92
	v_fmamk_f32 v93, v24, 0x3c088889, v202
	v_fmaak_f32 v93, v24, v93, 0x3e2aaaab
	v_fma_f32 v93, v24, v93, 0.5
	v_fma_f32 v93, v24, v93, 1.0
	v_mul_f32_e64 v93, v93, -v24
	v_sub_f32_e32 v92, 1.0, v92
	v_cmp_nlt_f32_e32 vcc, s5, v24
	s_nop 1
	v_cndmask_b32_e32 v76, v93, v92, vcc
	v_and_b32_e32 v24, 0xffff0000, v25
	v_add_f32_e32 v24, v3, v24
	v_mul_f32_e32 v24, 0xbfb8aa3b, v24
	v_exp_f32_e32 v24, v24
	s_nop 0
	v_add_f32_e32 v24, 1.0, v24
	v_rcp_f32_e32 v24, v24
	s_nop 0
	v_mul_f32_e32 v77, v70, v24
	v_mul_f32_e32 v24, 0x3fb17218, v77
	v_mul_f32_e32 v92, 0x3fb8aa3b, v24
	v_exp_f32_e32 v92, v92
	v_fmamk_f32 v93, v24, 0x3c088889, v202
	v_fmaak_f32 v93, v24, v93, 0x3e2aaaab
	v_fma_f32 v93, v24, v93, 0.5
	v_fma_f32 v93, v24, v93, 1.0
	v_mul_f32_e64 v93, v93, -v24
	v_sub_f32_e32 v92, 1.0, v92
	v_cmp_nlt_f32_e32 vcc, s5, v24
	s_nop 1
	v_cndmask_b32_e32 v61, v93, v92, vcc
	v_lshlrev_b32_e32 v24, 16, v26
	v_add_f32_e32 v24, v8, v24
	v_mul_f32_e32 v24, 0xbfb8aa3b, v24
	v_exp_f32_e32 v24, v24
	s_nop 0
	v_add_f32_e32 v24, 1.0, v24
	v_rcp_f32_e32 v24, v24
	s_nop 0
	v_mul_f32_e32 v78, v69, v24
	v_mul_f32_e32 v24, 0x3fb17218, v78
	v_mul_f32_e32 v92, 0x3fb8aa3b, v24
	v_exp_f32_e32 v92, v92
	v_fmamk_f32 v93, v24, 0x3c088889, v202
	v_fmaak_f32 v93, v24, v93, 0x3e2aaaab
	v_fma_f32 v93, v24, v93, 0.5
	v_fma_f32 v93, v24, v93, 1.0
	v_mul_f32_e64 v93, v93, -v24
	v_sub_f32_e32 v92, 1.0, v92
	v_cmp_nlt_f32_e32 vcc, s5, v24
	s_nop 1
	v_cndmask_b32_e32 v45, v93, v92, vcc
	v_and_b32_e32 v24, 0xffff0000, v26
	v_add_f32_e32 v24, v9, v24
	v_mul_f32_e32 v24, 0xbfb8aa3b, v24
	v_exp_f32_e32 v24, v24
	s_nop 0
	v_add_f32_e32 v24, 1.0, v24
	v_rcp_f32_e32 v24, v24
	s_nop 0
	v_mul_f32_e32 v47, v68, v24
	v_mul_f32_e32 v24, 0x3fb17218, v47
	v_mul_f32_e32 v92, 0x3fb8aa3b, v24
	v_exp_f32_e32 v92, v92
	v_fmamk_f32 v93, v24, 0x3c088889, v202
	v_fmaak_f32 v93, v24, v93, 0x3e2aaaab
	v_fma_f32 v93, v24, v93, 0.5
	v_fma_f32 v93, v24, v93, 1.0
	v_mul_f32_e64 v93, v93, -v24
	v_sub_f32_e32 v92, 1.0, v92
	v_cmp_nlt_f32_e32 vcc, s5, v24
	s_nop 1
	v_cndmask_b32_e32 v46, v93, v92, vcc
	v_lshlrev_b32_e32 v24, 16, v27
	v_add_f32_e32 v24, v10, v24
	v_mul_f32_e32 v24, 0xbfb8aa3b, v24
	v_exp_f32_e32 v24, v24
	s_nop 0
	v_add_f32_e32 v24, 1.0, v24
	v_rcp_f32_e32 v24, v24
	s_nop 0
	v_mul_f32_e32 v43, v67, v24
	v_mul_f32_e32 v24, 0x3fb17218, v43
	v_mul_f32_e32 v92, 0x3fb8aa3b, v24
	v_exp_f32_e32 v92, v92
	v_fmamk_f32 v93, v24, 0x3c088889, v202
	v_fmaak_f32 v93, v24, v93, 0x3e2aaaab
	v_fma_f32 v93, v24, v93, 0.5
	v_fma_f32 v93, v24, v93, 1.0
	v_mul_f32_e64 v93, v93, -v24
	v_sub_f32_e32 v92, 1.0, v92
	v_cmp_nlt_f32_e32 vcc, s5, v24
	s_nop 1
	v_cndmask_b32_e32 v42, v93, v92, vcc
	v_and_b32_e32 v24, 0xffff0000, v27
	v_add_f32_e32 v24, v11, v24
	v_mul_f32_e32 v24, 0xbfb8aa3b, v24
	v_exp_f32_e32 v24, v24
	s_nop 0
	v_add_f32_e32 v24, 1.0, v24
	v_rcp_f32_e32 v24, v24
	s_nop 0
	v_mul_f32_e32 v27, v75, v24
	v_mul_f32_e32 v24, 0x3fb17218, v27
	v_mul_f32_e32 v92, 0x3fb8aa3b, v24
	v_exp_f32_e32 v92, v92
	v_fmamk_f32 v93, v24, 0x3c088889, v202
	v_fmaak_f32 v93, v24, v93, 0x3e2aaaab
	v_fma_f32 v93, v24, v93, 0.5
	v_fma_f32 v93, v24, v93, 1.0
	v_mul_f32_e64 v93, v93, -v24
	v_sub_f32_e32 v92, 1.0, v92
	v_cmp_nlt_f32_e32 vcc, s5, v24
	s_nop 1
	v_cndmask_b32_e32 v26, v93, v92, vcc
	v_cmp_gt_f32_e32 vcc, s82, v43
	v_sqrt_f32_e32 v81, v42
	s_mov_b64 s[2:3], 0x13e01400
	v_cndmask_b32_e32 v55, 0, v221, vcc
	v_add_f32_e32 v43, v43, v55
	v_exp_f32_e32 v43, v43
	v_cndmask_b32_e32 v53, 0, v220, vcc
	v_cmp_gt_f32_e32 vcc, s82, v27
	v_lshl_add_u64 v[24:25], v[38:39], 0, s[2:3]
	v_ldexp_f32 v80, v43, v53
	s_waitcnt vmcnt(1)
	v_lshlrev_b32_e32 v43, 16, v19
	v_add_f32_e32 v43, v14, v43
	v_mul_f32_e32 v43, 0xbfb8aa3b, v43
	v_exp_f32_e32 v43, v43
	s_waitcnt vmcnt(0)
; __device__ __forceinline__ unsigned pk2(float lo, float hi) { f32x2_pk v = {lo, hi}; bf16x2_pk b = __builtin_convertvector(v, bf16x2_pk); return __builtin_bit_cast(unsigned, b); }
; __device__ __forceinline__ float sigmoidf_(float x) { return __builtin_amdgcn_rcpf(1.0f + __expf(-x)); }
; __device__ __forceinline__ void rg_unpack8(const u32x4 w, float* v) { v[0] = bflo(w.x); v[1] = bfhi(w.x); v[2] = bflo(w.y); v[3] = bfhi(w.y); v[4] = bflo(w.z); v[5] = bfhi(w.z); v[6] = bflo(w.w); v[7] = bfhi(w.w); }
; __device__ __forceinline__ void rg_ab(float ra, float ri, float x, float ba, float bx, float sp, float& a, float& b) {
;     const float r = sigmoidf_(ra + ba), ig = sigmoidf_(ri + bx); const float l2 = r * sp; a = exp2f(l2);
;     const float x2 = 1.3862943611198906f * l2;
;     const float om = x2 > -0.125f ? -x2 * (1.0f + x2 * (0.5f + x2 * (0.16666667f + x2 * (0.041666668f + x2 * 0.0083333338f)))) : 1.0f - __expf(x2);
;     b = __builtin_amdgcn_sqrtf(om) * (ig * x);
; }
; __device__ __forceinline__ void rg_scan2_phase(const bf16_t* RA0, bf16_t* RI0, const bf16_t* RA1, const bf16_t* RI1, const bf16_t* XCV, const float* bap, const float* bxp, const float* lamp, const float* CAR, bf16_t* Gb, int gtid, int ngt) {
;     ...
;         for (int i = 0; i < 64; ++i) { const size_t off = (size_t)(row0 + i) * DRNN + 8 * cg;
;             float ra[8], ri[8], xv[8]; rg_unpack8(*(const u32x4*)(RA0 + off), ra); rg_unpack8(*(const u32x4*)(RI0 + off), ri); rg_unpack8(*(const u32x4*)(XCV + off), xv);
; #pragma unroll
;             for (int e = 0; e < 8; ++e) { float a, bb; rg_ab(ra[e], ri[e], xv[e], ba[e], bx[e], sp[e], a, bb); h[e] = a * h[e] + bb; }
;             u32x4 o; o.x = pk2(h[0], h[1]); o.y = pk2(h[2], h[3]); o.z = pk2(h[4], h[5]); o.w = pk2(h[6], h[7]); *(u32x4*)(RI0 + off) = o; }
	v_lshlrev_b32_e32 v53, 16, v23
	v_add_f32_e32 v43, 1.0, v43
	v_rcp_f32_e32 v43, v43
	s_nop 0
	v_mul_f32_e32 v55, v43, v53
	v_cndmask_b32_e32 v53, 0, v221, vcc
	v_add_f32_e32 v27, v27, v53
	v_exp_f32_e32 v27, v27
	v_mul_f32_e32 v42, v55, v81
	v_pk_fma_f32 v[42:43], v[54:55], v[80:81], v[42:43] op_sel_hi:[1,1,0]
	v_sqrt_f32_e32 v81, v46
	v_cndmask_b32_e32 v43, 0, v220, vcc
	v_cmp_gt_f32_e32 vcc, s82, v47
	v_ldexp_f32 v54, v27, v43
	v_sqrt_f32_e32 v55, v26
	v_cndmask_b32_e32 v43, 0, v221, vcc
	v_add_f32_e32 v43, v47, v43
	v_exp_f32_e32 v43, v43
	v_cndmask_b32_e32 v27, 0, v220, vcc
	v_cmp_gt_f32_e32 vcc, s82, v78
	v_ldexp_f32 v80, v43, v27
	v_and_b32_e32 v27, 0xffff0000, v18
	v_add_f32_e32 v27, v13, v27
	v_mul_f32_e32 v27, 0xbfb8aa3b, v27
	v_lshlrev_b32_e32 v18, 16, v18
	v_exp_f32_e32 v27, v27
	v_add_f32_e32 v18, v12, v18
	v_mul_f32_e32 v18, 0xbfb8aa3b, v18
	v_exp_f32_e32 v18, v18
	v_add_f32_e32 v27, 1.0, v27
	v_rcp_f32_e32 v27, v27
	v_and_b32_e32 v43, 0xffff0000, v22
	v_add_f32_e32 v18, 1.0, v18
	v_rcp_f32_e32 v18, v18
	v_mul_f32_e32 v53, v27, v43
	v_cndmask_b32_e32 v43, 0, v221, vcc
	v_mul_f32_e32 v46, v53, v81
	v_cndmask_b32_e32 v27, 0, v220, vcc
	v_add_f32_e32 v43, v78, v43
	v_lshlrev_b32_e32 v22, 16, v22
	v_cmp_gt_f32_e32 vcc, s82, v77
	v_pk_fma_f32 v[46:47], v[52:53], v[80:81], v[46:47] op_sel_hi:[1,1,0]
	v_exp_f32_e32 v43, v43
	v_sqrt_f32_e32 v53, v45
	v_mul_f32_e32 v45, v18, v22
	v_cndmask_b32_e32 v22, 0, v221, vcc
	v_add_f32_e32 v22, v77, v22
	v_exp_f32_e32 v22, v22
	v_ldexp_f32 v52, v43, v27
	v_mul_f32_e32 v18, v45, v53
	v_pk_fma_f32 v[52:53], v[44:45], v[52:53], v[18:19] op_sel_hi:[1,1,0]
	v_cndmask_b32_e32 v18, 0, v220, vcc
	v_ldexp_f32 v44, v22, v18
	v_and_b32_e32 v18, 0xffff0000, v17
	v_add_f32_e32 v18, v7, v18
	v_mul_f32_e32 v18, 0xbfb8aa3b, v18
	v_exp_f32_e32 v18, v18
	v_lshlrev_b32_e32 v17, 16, v17
	v_add_f32_e32 v17, v6, v17
	v_mul_f32_e32 v17, 0xbfb8aa3b, v17
	v_add_f32_e32 v18, 1.0, v18
	v_rcp_f32_e32 v18, v18
	v_exp_f32_e32 v17, v17
	v_and_b32_e32 v22, 0xffff0000, v21
	v_sqrt_f32_e32 v45, v61
	v_cmp_gt_f32_e32 vcc, s82, v59
	v_mul_f32_e32 v61, v18, v22
	v_add_f32_e32 v17, 1.0, v17
	v_cndmask_b32_e32 v22, 0, v221, vcc
	v_add_f32_e32 v22, v59, v22
	v_exp_f32_e32 v22, v22
	v_mul_f32_e32 v18, v61, v45
	v_rcp_f32_e32 v17, v17
	v_pk_fma_f32 v[60:61], v[60:61], v[44:45], v[18:19] op_sel_hi:[1,1,0]
	v_sqrt_f32_e32 v45, v76
	v_cndmask_b32_e32 v18, 0, v220, vcc
	v_ldexp_f32 v44, v22, v18
	v_lshlrev_b32_e32 v18, 16, v21
	v_mul_f32_e32 v59, v17, v18
	v_mul_f32_e32 v18, v59, v45
	v_cmp_gt_f32_e32 vcc, s82, v57
	v_pk_fma_f32 v[44:45], v[58:59], v[44:45], v[18:19] op_sel_hi:[1,1,0]
	v_sqrt_f32_e32 v59, v62
	v_cndmask_b32_e32 v18, 0, v221, vcc
	v_add_f32_e32 v18, v57, v18
	v_exp_f32_e32 v18, v18
	v_cndmask_b32_e32 v17, 0, v220, vcc
	v_mov_b32_e32 v76, v63
	v_cmp_gt_f32_e32 vcc, s82, v31
	v_ldexp_f32 v58, v18, v17
	v_and_b32_e32 v17, 0xffff0000, v16
	v_add_f32_e32 v17, v5, v17
	v_mul_f32_e32 v17, 0xbfb8aa3b, v17
	v_exp_f32_e32 v17, v17
	v_and_b32_e32 v18, 0xffff0000, v20
	v_add_f32_e32 v17, 1.0, v17
	v_rcp_f32_e32 v17, v17
	s_nop 0
	v_mul_f32_e32 v77, v17, v18
	v_lshlrev_b32_e32 v17, 16, v16
	v_mul_f32_e32 v18, v63, v58
	v_add_f32_e32 v17, v4, v17
	v_pk_fma_f32 v[58:59], v[76:77], v[58:59], v[18:19] op_sel_hi:[1,1,0]
	v_lshlrev_b32_e32 v18, 16, v20
	v_cndmask_b32_e32 v20, 0, v221, vcc
	v_mul_f32_e32 v17, 0xbfb8aa3b, v17
	v_add_f32_e32 v20, v31, v20
	v_exp_f32_e32 v17, v17
	v_exp_f32_e32 v20, v20
	v_cndmask_b32_e32 v16, 0, v220, vcc
	v_add_f32_e32 v17, 1.0, v17
	v_ldexp_f32 v16, v20, v16
	v_rcp_f32_e32 v20, v17
	v_sqrt_f32_e32 v17, v51
	v_mul_f32_e32 v57, v20, v18
	v_mul_f32_e32 v18, v57, v17
	v_pk_fma_f32 v[56:57], v[56:57], v[16:17], v[18:19] op_sel_hi:[1,1,0]
	v_and_b32_e32 v16, 0xffff0000, v19
	v_add_f32_e32 v16, v15, v16
	v_mul_f32_e32 v16, 0xbfb8aa3b, v16
	v_exp_f32_e32 v16, v16
	v_and_b32_e32 v17, 0xffff0000, v23
	v_cvt_pk_bf16_f32 v18, v52, v46
	global_load_dwordx4 v[20:23], v[40:41], off offset:3584
	v_add_f32_e32 v16, 1.0, v16
	v_rcp_f32_e32 v16, v16
	s_nop 0
	v_mul_f32_e32 v51, v16, v17
	v_mul_f32_e32 v16, v51, v55
	v_pk_fma_f32 v[54:55], v[50:51], v[54:55], v[16:17] op_sel_hi:[1,1,0]
	v_cvt_pk_bf16_f32 v16, v56, v59
	v_cvt_pk_bf16_f32 v17, v44, v60
	v_cvt_pk_bf16_f32 v19, v42, v54
	global_store_dwordx4 v[24:25], v[16:19], off
	s_nop 1
	v_mov_b32_e32 v24, v162
	v_mov_b32_e32 v25, v163
	v_mov_b32_e32 v26, v164
	v_mov_b32_e32 v27, v165
	v_lshl_add_u64 v[166:167], v[48:49], 0, s[100:101]
	global_load_dwordx4 v[162:165], v[166:167], off offset:2048
	s_waitcnt vmcnt(1)
; __device__ __forceinline__ unsigned pk2(float lo, float hi) { f32x2_pk v = {lo, hi}; bf16x2_pk b = __builtin_convertvector(v, bf16x2_pk); return __builtin_bit_cast(unsigned, b); }
; __device__ __forceinline__ float sigmoidf_(float x) { return __builtin_amdgcn_rcpf(1.0f + __expf(-x)); }
; __device__ __forceinline__ void rg_unpack8(const u32x4 w, float* v) { v[0] = bflo(w.x); v[1] = bfhi(w.x); v[2] = bflo(w.y); v[3] = bfhi(w.y); v[4] = bflo(w.z); v[5] = bfhi(w.z); v[6] = bflo(w.w); v[7] = bfhi(w.w); }
; __device__ __forceinline__ void rg_ab(float ra, float ri, float x, float ba, float bx, float sp, float& a, float& b) {
;     const float r = sigmoidf_(ra + ba), ig = sigmoidf_(ri + bx); const float l2 = r * sp; a = exp2f(l2);
;     const float x2 = 1.3862943611198906f * l2;
;     const float om = x2 > -0.125f ? -x2 * (1.0f + x2 * (0.5f + x2 * (0.16666667f + x2 * (0.041666668f + x2 * 0.0083333338f)))) : 1.0f - __expf(x2);
;     b = __builtin_amdgcn_sqrtf(om) * (ig * x);
; }
; __device__ __forceinline__ void rg_scan2_phase(const bf16_t* RA0, bf16_t* RI0, const bf16_t* RA1, const bf16_t* RI1, const bf16_t* XCV, const float* bap, const float* bxp, const float* lamp, const float* CAR, bf16_t* Gb, int gtid, int ngt) {
;     ...
;         for (int i = 0; i < 64; ++i) { const size_t off = (size_t)(row0 + i) * DRNN + 8 * cg;
;             float ra[8], ri[8], xv[8]; rg_unpack8(*(const u32x4*)(RA0 + off), ra); rg_unpack8(*(const u32x4*)(RI0 + off), ri); rg_unpack8(*(const u32x4*)(XCV + off), xv);
; #pragma unroll
;             for (int e = 0; e < 8; ++e) { float a, bb; rg_ab(ra[e], ri[e], xv[e], ba[e], bx[e], sp[e], a, bb); h[e] = a * h[e] + bb; }
;             u32x4 o; o.x = pk2(h[0], h[1]); o.y = pk2(h[2], h[3]); o.z = pk2(h[4], h[5]); o.w = pk2(h[6], h[7]); *(u32x4*)(RI0 + off) = o; }
	v_lshlrev_b32_e32 v31, 16, v24
	v_add_co_u32_e32 v16, vcc, 0x8a01000, v38
	v_add_f32_e32 v31, v0, v31
	s_nop 0
	v_addc_co_u32_e32 v17, vcc, 0, v39, vcc
	global_load_dwordx4 v[16:19], v[16:17], off offset:3584
	v_mul_f32_e32 v31, 0xbfb8aa3b, v31
	v_exp_f32_e32 v31, v31
	s_nop 0
	v_add_f32_e32 v31, 1.0, v31
	v_rcp_f32_e32 v31, v31
	s_nop 0
	v_mul_f32_e32 v31, v74, v31
	v_mul_f32_e32 v41, 0x3fb17218, v31
	v_mul_f32_e32 v92, 0x3fb8aa3b, v41
	v_exp_f32_e32 v92, v92
	v_fmamk_f32 v93, v41, 0x3c088889, v202
	v_fmaak_f32 v93, v41, v93, 0x3e2aaaab
	v_fma_f32 v93, v41, v93, 0.5
	v_fma_f32 v93, v41, v93, 1.0
	v_mul_f32_e64 v93, v93, -v41
	v_sub_f32_e32 v92, 1.0, v92
	v_cmp_nlt_f32_e32 vcc, s5, v41
	s_nop 1
	v_cndmask_b32_e32 v40, v93, v92, vcc
	v_and_b32_e32 v24, 0xffff0000, v24
	v_add_f32_e32 v24, v1, v24
	v_mul_f32_e32 v24, 0xbfb8aa3b, v24
	v_exp_f32_e32 v24, v24
	s_nop 0
	v_add_f32_e32 v24, 1.0, v24
	v_rcp_f32_e32 v24, v24
	s_nop 0
	v_mul_f32_e32 v24, v73, v24
	v_mul_f32_e32 v41, 0x3fb17218, v24
	v_mul_f32_e32 v92, 0x3fb8aa3b, v41
	v_exp_f32_e32 v92, v92
	v_fmamk_f32 v93, v41, 0x3c088889, v202
	v_fmaak_f32 v93, v41, v93, 0x3e2aaaab
	v_fma_f32 v93, v41, v93, 0.5
	v_fma_f32 v93, v41, v93, 1.0
	v_mul_f32_e64 v93, v93, -v41
	v_sub_f32_e32 v92, 1.0, v92
	v_cmp_nlt_f32_e32 vcc, s5, v41
	s_nop 1
	v_cndmask_b32_e32 v43, v93, v92, vcc
	v_lshlrev_b32_e32 v41, 16, v25
	v_add_f32_e32 v41, v2, v41
	v_mul_f32_e32 v41, 0xbfb8aa3b, v41
	v_exp_f32_e32 v41, v41
	s_nop 0
	v_add_f32_e32 v41, 1.0, v41
	v_rcp_f32_e32 v41, v41
	s_nop 0
	v_mul_f32_e32 v45, v71, v41
	v_mul_f32_e32 v41, 0x3fb17218, v45
	v_mul_f32_e32 v92, 0x3fb8aa3b, v41
	v_exp_f32_e32 v92, v92
	v_fmamk_f32 v93, v41, 0x3c088889, v202
	v_fmaak_f32 v93, v41, v93, 0x3e2aaaab
	v_fma_f32 v93, v41, v93, 0.5
	v_fma_f32 v93, v41, v93, 1.0
	v_mul_f32_e64 v93, v93, -v41
	v_sub_f32_e32 v92, 1.0, v92
	v_cmp_nlt_f32_e32 vcc, s5, v41
	s_nop 1
	v_cndmask_b32_e32 v47, v93, v92, vcc
	v_and_b32_e32 v25, 0xffff0000, v25
	v_add_f32_e32 v25, v3, v25
	v_mul_f32_e32 v25, 0xbfb8aa3b, v25
	v_exp_f32_e32 v25, v25
	s_nop 0
	v_add_f32_e32 v25, 1.0, v25
	v_rcp_f32_e32 v25, v25
	s_nop 0
	v_mul_f32_e32 v25, v70, v25
	v_mul_f32_e32 v41, 0x3fb17218, v25
	v_mul_f32_e32 v92, 0x3fb8aa3b, v41
	v_exp_f32_e32 v92, v92
	v_fmamk_f32 v93, v41, 0x3c088889, v202
	v_fmaak_f32 v93, v41, v93, 0x3e2aaaab
	v_fma_f32 v93, v41, v93, 0.5
	v_fma_f32 v93, v41, v93, 1.0
	v_mul_f32_e64 v93, v93, -v41
	v_sub_f32_e32 v92, 1.0, v92
	v_cmp_nlt_f32_e32 vcc, s5, v41
	s_nop 1
	v_cndmask_b32_e32 v48, v93, v92, vcc
	v_lshlrev_b32_e32 v41, 16, v26
	v_add_f32_e32 v41, v8, v41
	v_mul_f32_e32 v41, 0xbfb8aa3b, v41
	v_exp_f32_e32 v41, v41
	s_nop 0
	v_add_f32_e32 v41, 1.0, v41
	v_rcp_f32_e32 v41, v41
	s_nop 0
	v_mul_f32_e32 v49, v69, v41
	v_mul_f32_e32 v41, 0x3fb17218, v49
	v_mul_f32_e32 v92, 0x3fb8aa3b, v41
	v_exp_f32_e32 v92, v92
	v_fmamk_f32 v93, v41, 0x3c088889, v202
	v_fmaak_f32 v93, v41, v93, 0x3e2aaaab
	v_fma_f32 v93, v41, v93, 0.5
	v_fma_f32 v93, v41, v93, 1.0
	v_mul_f32_e64 v93, v93, -v41
	v_sub_f32_e32 v92, 1.0, v92
	v_cmp_nlt_f32_e32 vcc, s5, v41
	s_nop 1
	v_cndmask_b32_e32 v53, v93, v92, vcc
	v_and_b32_e32 v26, 0xffff0000, v26
	v_add_f32_e32 v26, v9, v26
	v_mul_f32_e32 v26, 0xbfb8aa3b, v26
	v_exp_f32_e32 v26, v26
	s_nop 0
	v_add_f32_e32 v26, 1.0, v26
	v_rcp_f32_e32 v26, v26
	s_nop 0
	v_mul_f32_e32 v26, v68, v26
	v_mul_f32_e32 v41, 0x3fb17218, v26
	v_mul_f32_e32 v92, 0x3fb8aa3b, v41
	v_exp_f32_e32 v92, v92
	v_fmamk_f32 v93, v41, 0x3c088889, v202
	v_fmaak_f32 v93, v41, v93, 0x3e2aaaab
	v_fma_f32 v93, v41, v93, 0.5
	v_fma_f32 v93, v41, v93, 1.0
	v_mul_f32_e64 v93, v93, -v41
	v_sub_f32_e32 v92, 1.0, v92
	v_cmp_nlt_f32_e32 vcc, s5, v41
	s_nop 1
	v_cndmask_b32_e32 v55, v93, v92, vcc
	v_lshlrev_b32_e32 v41, 16, v27
	v_add_f32_e32 v41, v10, v41
	v_mul_f32_e32 v41, 0xbfb8aa3b, v41
	v_exp_f32_e32 v41, v41
	s_nop 0
	v_add_f32_e32 v41, 1.0, v41
	v_rcp_f32_e32 v41, v41
	s_nop 0
	v_mul_f32_e32 v58, v67, v41
	v_mul_f32_e32 v41, 0x3fb17218, v58
	v_mul_f32_e32 v92, 0x3fb8aa3b, v41
	v_exp_f32_e32 v92, v92
	v_fmamk_f32 v93, v41, 0x3c088889, v202
	v_fmaak_f32 v93, v41, v93, 0x3e2aaaab
	v_fma_f32 v93, v41, v93, 0.5
	v_fma_f32 v93, v41, v93, 1.0
	v_mul_f32_e64 v93, v93, -v41
	v_sub_f32_e32 v92, 1.0, v92
	v_cmp_nlt_f32_e32 vcc, s5, v41
	s_nop 1
	v_cndmask_b32_e32 v62, v93, v92, vcc
	v_and_b32_e32 v27, 0xffff0000, v27
	v_add_f32_e32 v27, v11, v27
	v_mul_f32_e32 v27, 0xbfb8aa3b, v27
	v_exp_f32_e32 v27, v27
	s_nop 0
	v_add_f32_e32 v27, 1.0, v27
	v_rcp_f32_e32 v27, v27
	s_nop 0
	v_mul_f32_e32 v27, v75, v27
	v_mul_f32_e32 v41, 0x3fb17218, v27
	v_cmp_nlt_f32_e32 vcc, s5, v41
	s_and_saveexec_b64 s[2:3], vcc
	s_xor_b64 s[24:25], exec, s[2:3]
	v_mul_f32_e32 v41, 0x3fb8aa3b, v41
	v_exp_f32_e32 v41, v41
	s_nop 0
	v_sub_f32_e32 v63, 1.0, v41
	s_andn2_saveexec_b64 s[24:25], s[24:25]
	s_cbranch_execz .LBB0_1250
	v_fmamk_f32 v50, v41, 0x3c088889, v202
	v_fmaak_f32 v50, v41, v50, 0x3e2aaaab
	v_fma_f32 v50, v41, v50, 0.5
	v_fma_f32 v50, v41, v50, 1.0
	v_mul_f32_e64 v63, v50, -v41
	s_branch .LBB0_1250
